# P2 item start: 64-lane prefix sum of g via DPP row_shr/row_bcast scan (7 VALU) instead of six serial ds_bpermute round trips executed by one wave while seven wait
# speedup vs baseline: 1.0117x; 1.0027x over previous
; __device__ __forceinline__ void gdn_prep_item(const Params& p, unsigned char* lds, int item, u32x4 (&raw)[3][2][4], float& gpre, float& bpre, int next_item) {
;     ...
;     if (wave == 0) {
;         float g = gpre; const float be = bpre;
; #pragma unroll
;         for (int o = 1; o < 64; o <<= 1) { const float t = __shfl_up(g, o); if (lane >= o) g += t; }
;         gcs[lane] = g; bets[lane] = be;
;         if (lane == 63) ((float*)(dob + DO_GL))[item] = __expf(g);
;     }
.LBB0_103:
	s_and_saveexec_b64 s[20:21], s[4:5]
	s_cbranch_execz .LBB0_106
	s_waitcnt vmcnt(1)
	v_add_f32_dpp v1, v172, v172 row_shr:1 row_mask:0xf bank_mask:0xf bound_ctrl:1
	v_add_f32_dpp v1, v172, v1 row_shr:2 row_mask:0xf bank_mask:0xf bound_ctrl:1
	v_add_f32_dpp v1, v172, v1 row_shr:3 row_mask:0xf bank_mask:0xf bound_ctrl:1
	s_nop 1
	v_add_f32_dpp v1, v1, v1 row_shr:4 row_mask:0xf bank_mask:0xe
	s_nop 1
	v_add_f32_dpp v1, v1, v1 row_shr:8 row_mask:0xf bank_mask:0xc
	s_nop 1
	v_add_f32_dpp v1, v1, v1 row_bcast:15 row_mask:0xa bank_mask:0xf
	s_nop 1
	v_add_f32_dpp v1, v1, v1 row_bcast:31 row_mask:0xc bank_mask:0xf
	v_mov_b32_e32 v0, v1
	ds_write_b32 v140, v1
	s_waitcnt vmcnt(0)
	ds_write_b32 v141, v173
	s_and_b64 exec, exec, s[16:17]
	s_cbranch_execz .LBB0_106
	v_mul_f32_e32 v0, 0x3fb8aa3b, v0
	v_exp_f32_e32 v0, v0
	global_store_dword v16, v0, s[88:89]
